# nt (non-temporal) hint on the P1-U and P6 GEMM epilogue stores so streamed outputs do not displace A/B tiles in L2
# speedup vs baseline: 1.0281x; 1.0020x over previous
.LBB0_404:
	v_lshrrev_b32_e32 v130, 2, v128
	v_readlane_b32 s1, v253, 10
	v_and_b32_e32 v130, 8, v130
	v_and_b32_e32 v128, 16, v128
	s_add_i32 s4, s4, s1
	v_readlane_b32 s1, v253, 18
	v_or_b32_e32 v132, s4, v150
	v_cvt_pk_bf16_f32 v96, v96, v97
	v_or3_b32 v128, v128, v130, s1
	v_or_b32_e32 v130, s0, v128
	v_readlane_b32 s0, v253, 19
	v_ashrrev_i32_e32 v131, 31, v130
	v_readlane_b32 s1, v253, 20
	v_cvt_pk_bf16_f32 v97, v98, v99
	v_cvt_pk_bf16_f32 v98, v100, v101
	v_lshl_add_u64 v[130:131], v[130:131], 1, s[0:1]
	v_or_b32_e32 v100, 48, v132
	v_cvt_pk_bf16_f32 v56, v56, v57
	v_cvt_pk_bf16_f32 v57, v58, v59
	v_cvt_pk_bf16_f32 v58, v60, v61
	v_cvt_pk_bf16_f32 v59, v62, v63
	v_mad_i64_i32 v[100:101], s[0:1], v100, s86, v[130:131]
	v_permlane16_swap_b32_e32 v56, v58
	v_permlane16_swap_b32_e32 v57, v59
	v_cvt_pk_bf16_f32 v120, v120, v121
	v_cvt_pk_bf16_f32 v121, v122, v123
	v_cvt_pk_bf16_f32 v122, v124, v125
	v_cvt_pk_bf16_f32 v123, v126, v127
	v_cvt_pk_bf16_f32 v112, v112, v113
	v_cvt_pk_bf16_f32 v113, v114, v115
	v_cvt_pk_bf16_f32 v114, v116, v117
	v_cvt_pk_bf16_f32 v115, v118, v119
	v_or_b32_e32 v116, 16, v132
	v_cvt_pk_bf16_f32 v104, v104, v105
	v_cvt_pk_bf16_f32 v105, v106, v107
	v_cvt_pk_bf16_f32 v106, v108, v109
	v_cvt_pk_bf16_f32 v107, v110, v111
	v_or_b32_e32 v108, 32, v132
	v_cvt_pk_bf16_f32 v99, v102, v103
	v_cvt_pk_bf16_f32 v88, v88, v89
	v_cvt_pk_bf16_f32 v89, v90, v91
	v_cvt_pk_bf16_f32 v90, v92, v93
	v_cvt_pk_bf16_f32 v91, v94, v95
	v_cvt_pk_bf16_f32 v80, v80, v81
	v_cvt_pk_bf16_f32 v81, v82, v83
	v_cvt_pk_bf16_f32 v82, v84, v85
	v_cvt_pk_bf16_f32 v83, v86, v87
	v_cvt_pk_bf16_f32 v72, v72, v73
	v_cvt_pk_bf16_f32 v73, v74, v75
	v_cvt_pk_bf16_f32 v74, v76, v77
	v_cvt_pk_bf16_f32 v75, v78, v79
	global_store_dwordx4 v[100:101], v[56:59], off offset:256 nt
	v_add_u32_e32 v60, 0x80, v132
	v_cvt_pk_bf16_f32 v48, v48, v49
	v_cvt_pk_bf16_f32 v56, v64, v65
	v_cvt_pk_bf16_f32 v57, v66, v67
	v_cvt_pk_bf16_f32 v58, v68, v69
	v_cvt_pk_bf16_f32 v59, v70, v71
	v_cvt_pk_bf16_f32 v49, v50, v51
	v_cvt_pk_bf16_f32 v50, v52, v53
	v_cvt_pk_bf16_f32 v51, v54, v55
	v_add_u32_e32 v52, 0x90, v132
	v_cvt_pk_bf16_f32 v40, v40, v41
	v_cvt_pk_bf16_f32 v41, v42, v43
	v_cvt_pk_bf16_f32 v42, v44, v45
	v_cvt_pk_bf16_f32 v43, v46, v47
	v_add_u32_e32 v44, 0xa0, v132
	v_cvt_pk_bf16_f32 v32, v32, v33
	v_cvt_pk_bf16_f32 v33, v34, v35
	v_cvt_pk_bf16_f32 v34, v36, v37
	v_cvt_pk_bf16_f32 v35, v38, v39
	v_add_u32_e32 v36, 0xb0, v132
	v_cvt_pk_bf16_f32 v24, v24, v25
	v_cvt_pk_bf16_f32 v25, v26, v27
	v_cvt_pk_bf16_f32 v26, v28, v29
	v_cvt_pk_bf16_f32 v27, v30, v31
	v_cvt_pk_bf16_f32 v16, v16, v17
	v_cvt_pk_bf16_f32 v17, v18, v19
	v_cvt_pk_bf16_f32 v18, v20, v21
	v_cvt_pk_bf16_f32 v19, v22, v23
	v_cvt_pk_bf16_f32 v8, v8, v9
	v_cvt_pk_bf16_f32 v9, v10, v11
	v_cvt_pk_bf16_f32 v10, v12, v13
	v_cvt_pk_bf16_f32 v11, v14, v15
	v_cvt_pk_bf16_f32 v0, v0, v1
	v_cvt_pk_bf16_f32 v1, v2, v3
	v_cvt_pk_bf16_f32 v2, v4, v5
	v_cvt_pk_bf16_f32 v3, v6, v7
	v_permlane16_swap_b32_e32 v120, v122
	v_permlane16_swap_b32_e32 v121, v123
	v_mad_i64_i32 v[124:125], s[0:1], v132, s86, v[130:131]
	v_permlane16_swap_b32_e32 v112, v114
	v_permlane16_swap_b32_e32 v113, v115
	v_mad_i64_i32 v[116:117], s[0:1], v116, s86, v[130:131]
	v_permlane16_swap_b32_e32 v104, v106
	v_permlane16_swap_b32_e32 v105, v107
	v_mad_i64_i32 v[108:109], s[0:1], v108, s86, v[130:131]
	v_permlane16_swap_b32_e32 v96, v98
	v_permlane16_swap_b32_e32 v97, v99
	v_permlane16_swap_b32_e32 v88, v90
	v_permlane16_swap_b32_e32 v89, v91
	v_permlane16_swap_b32_e32 v80, v82
	v_permlane16_swap_b32_e32 v81, v83
	v_permlane16_swap_b32_e32 v72, v74
	v_permlane16_swap_b32_e32 v73, v75
	v_permlane16_swap_b32_e32 v56, v58
	v_permlane16_swap_b32_e32 v57, v59
	v_mad_i64_i32 v[60:61], s[0:1], v60, s86, v[130:131]
	v_permlane16_swap_b32_e32 v48, v50
	v_permlane16_swap_b32_e32 v49, v51
	v_mad_i64_i32 v[52:53], s[0:1], v52, s86, v[130:131]
	v_permlane16_swap_b32_e32 v40, v42
	v_permlane16_swap_b32_e32 v41, v43
	v_mad_i64_i32 v[44:45], s[0:1], v44, s86, v[130:131]
	v_permlane16_swap_b32_e32 v32, v34
	v_permlane16_swap_b32_e32 v33, v35
	v_mad_i64_i32 v[36:37], s[0:1], v36, s86, v[130:131]
	v_permlane16_swap_b32_e32 v24, v26
	v_permlane16_swap_b32_e32 v25, v27
	v_permlane16_swap_b32_e32 v16, v18
	v_permlane16_swap_b32_e32 v17, v19
	v_permlane16_swap_b32_e32 v8, v10
	v_permlane16_swap_b32_e32 v9, v11
	v_permlane16_swap_b32_e32 v0, v2
	v_permlane16_swap_b32_e32 v1, v3
	global_store_dwordx4 v[124:125], v[120:123], off nt
	global_store_dwordx4 v[116:117], v[112:115], off nt
	global_store_dwordx4 v[108:109], v[104:107], off nt
	global_store_dwordx4 v[100:101], v[96:99], off nt
	global_store_dwordx4 v[124:125], v[88:91], off offset:256 nt
	global_store_dwordx4 v[116:117], v[80:83], off offset:256 nt
	global_store_dwordx4 v[108:109], v[72:75], off offset:256 nt
	global_store_dwordx4 v[60:61], v[56:59], off nt
	global_store_dwordx4 v[52:53], v[48:51], off nt
	global_store_dwordx4 v[44:45], v[40:43], off nt
	global_store_dwordx4 v[36:37], v[32:35], off nt
	global_store_dwordx4 v[60:61], v[24:27], off offset:256 nt
	global_store_dwordx4 v[52:53], v[16:19], off offset:256 nt
	global_store_dwordx4 v[44:45], v[8:11], off offset:256 nt
	global_store_dwordx4 v[36:37], v[0:3], off offset:256 nt

.LBB0_629:
	s_cmp_eq_u32 s25, 3
	s_mov_b32 s0, 0xa000000
	s_cselect_b32 s0, s0, 0xc000000
	s_add_u32 s0, s76, s0
	v_lshrrev_b32_e32 v130, 2, v128
	v_readlane_b32 s26, v253, 18
	s_addc_u32 s1, s77, 0
	v_and_b32_e32 v130, 8, v130
	s_add_i32 s25, s52, s27
	s_or_b32 s8, s8, s26
	v_and_or_b32 v128, v128, 16, v130
	v_or_b32_e32 v131, s8, v147
	v_mov_b32_e32 v132, s25
	s_movk_i32 s8, 0x7d8
	v_or_b32_e32 v130, s25, v128
	v_bitop3_b32 v132, v128, s8, v132 bitop3:0xc8
	s_ashr_i32 s25, s25, 9
	s_lshl_b32 s8, s24, 1
	s_and_b32 s33, s25, -4
	s_and_b32 s24, s8, 2
	s_or_b32 s28, s24, s33
	s_ashr_i32 s29, s28, 31
	v_cvt_pk_bf16_f32 v120, v120, v121
	v_cvt_pk_bf16_f32 v121, v122, v123
	v_cvt_pk_bf16_f32 v122, v124, v125
	s_lshl_b64 s[28:29], s[28:29], 19
	v_lshlrev_b32_e32 v124, 12, v131
	s_add_u32 s28, s0, s28
	v_and_b32_e32 v128, 0x6f000, v124
	s_addc_u32 s29, s1, s29
	v_cvt_pk_bf16_f32 v112, v112, v113
	v_cvt_pk_bf16_f32 v113, v114, v115
	v_cvt_pk_bf16_f32 v114, v116, v117
	v_or_b32_e32 v116, 0x10000, v128
	v_mov_b32_e32 v117, v129
	s_or_b32 s8, s24, 1
	v_lshl_add_u64 v[124:125], s[28:29], 0, v[128:129]
	v_cvt_pk_bf16_f32 v115, v118, v119
	v_lshl_add_u64 v[118:119], s[28:29], 0, v[116:117]
	s_or_b32 s28, s8, s33
	s_ashr_i32 s29, s28, 31
	s_lshl_b64 s[28:29], s[28:29], 19
	v_cvt_pk_bf16_f32 v123, v126, v127
	v_lshlrev_b32_e32 v126, 1, v132
	v_mov_b32_e32 v127, v129
	v_cvt_pk_bf16_f32 v88, v88, v89
	v_cvt_pk_bf16_f32 v89, v90, v91
	v_cvt_pk_bf16_f32 v90, v96, v97
	v_cvt_pk_bf16_f32 v91, v98, v99
	s_add_u32 s28, s0, s28
	v_lshl_add_u64 v[118:119], v[118:119], 0, v[126:127]
	v_permlane16_swap_b32_e32 v88, v90
	v_permlane16_swap_b32_e32 v89, v91
	s_addc_u32 s29, s1, s29
	global_store_dwordx4 v[118:119], v[88:91], off offset:64 nt
	v_cvt_pk_bf16_f32 v80, v80, v81
	v_cvt_pk_bf16_f32 v81, v82, v83
	v_cvt_pk_bf16_f32 v88, v92, v93
	v_cvt_pk_bf16_f32 v89, v94, v95
	v_cvt_pk_bf16_f32 v90, v100, v101
	v_cvt_pk_bf16_f32 v91, v102, v103
	v_lshl_add_u64 v[92:93], s[28:29], 0, v[128:129]
	v_permlane16_swap_b32_e32 v88, v90
	v_permlane16_swap_b32_e32 v89, v91
	v_lshl_add_u64 v[92:93], v[92:93], 0, v[126:127]
	v_cvt_pk_bf16_f32 v83, v86, v87
	v_or_b32_e32 v86, 0x90, v131
	global_store_dwordx4 v[92:93], v[88:91], off nt
	v_cvt_pk_bf16_f32 v82, v84, v85
	v_mov_b32_e32 v87, v129
	v_lshrrev_b32_e32 v88, 7, v86
	v_bfi_b32 v84, 3, v88, s25
	v_ashrrev_i32_e32 v85, 31, v84
	v_lshlrev_b64 v[84:85], 19, v[84:85]
	v_lshlrev_b32_e32 v86, 12, v86
	v_lshl_add_u64 v[84:85], s[0:1], 0, v[84:85]
	v_and_b32_e32 v86, 0x7f000, v86
	v_cvt_pk_bf16_f32 v104, v104, v105
	v_cvt_pk_bf16_f32 v105, v106, v107
	v_cvt_pk_bf16_f32 v106, v108, v109
	v_cvt_pk_bf16_f32 v107, v110, v111
	v_lshl_add_u64 v[84:85], v[84:85], 0, v[86:87]
	v_cvt_pk_bf16_f32 v72, v72, v73
	v_cvt_pk_bf16_f32 v73, v74, v75
	v_cvt_pk_bf16_f32 v74, v76, v77
	v_cvt_pk_bf16_f32 v75, v78, v79
	v_cvt_pk_bf16_f32 v56, v56, v57
	v_cvt_pk_bf16_f32 v57, v58, v59
	v_cvt_pk_bf16_f32 v58, v64, v65
	v_cvt_pk_bf16_f32 v59, v66, v67
	v_permlane16_swap_b32_e32 v120, v122
	v_permlane16_swap_b32_e32 v121, v123
	v_lshl_add_u64 v[124:125], v[124:125], 0, v[126:127]
	v_permlane16_swap_b32_e32 v112, v114
	v_permlane16_swap_b32_e32 v113, v115
	v_permlane16_swap_b32_e32 v104, v106
	v_permlane16_swap_b32_e32 v105, v107
	v_permlane16_swap_b32_e32 v80, v82
	v_permlane16_swap_b32_e32 v81, v83
	v_lshl_add_u64 v[84:85], v[84:85], 0, v[126:127]
	v_permlane16_swap_b32_e32 v72, v74
	v_permlane16_swap_b32_e32 v73, v75
	v_permlane16_swap_b32_e32 v56, v58
	v_permlane16_swap_b32_e32 v57, v59
	global_store_dwordx4 v[124:125], v[120:123], off nt
	global_store_dwordx4 v[118:119], v[112:115], off nt
	global_store_dwordx4 v[124:125], v[104:107], off offset:64 nt
	global_store_dwordx4 v[84:85], v[80:83], off nt
	global_store_dwordx4 v[92:93], v[72:75], off offset:64 nt
	global_store_dwordx4 v[84:85], v[56:59], off offset:64 nt
	v_mov_b32_e32 v65, v129
	v_cvt_pk_bf16_f32 v48, v48, v49
	v_add_u32_e32 v56, 0x80, v130
	v_ashrrev_i32_e32 v66, 9, v56
	v_and_b32_e32 v67, -4, v66
	v_and_b32_e32 v64, 0x7d8, v56
	v_cvt_pk_bf16_f32 v56, v60, v61
	v_or_b32_e32 v60, s24, v67
	v_ashrrev_i32_e32 v61, 31, v60
	v_lshlrev_b64 v[60:61], 19, v[60:61]
	v_lshl_add_u64 v[60:61], s[0:1], 0, v[60:61]
	v_lshlrev_b32_e32 v64, 1, v64
	v_cvt_pk_bf16_f32 v49, v50, v51
	v_cvt_pk_bf16_f32 v50, v52, v53
	v_cvt_pk_bf16_f32 v51, v54, v55
	v_lshl_add_u64 v[52:53], v[60:61], 0, v[116:117]
	v_permlane16_swap_b32_e32 v48, v50
	v_permlane16_swap_b32_e32 v49, v51
	v_lshl_add_u64 v[52:53], v[52:53], 0, v[64:65]
	global_store_dwordx4 v[52:53], v[48:51], off nt
	v_cvt_pk_bf16_f32 v40, v40, v41
	v_cvt_pk_bf16_f32 v41, v42, v43
	v_add_u32_e32 v48, 0xa0, v130
	v_ashrrev_i32_e32 v50, 9, v48
	v_and_b32_e32 v51, -4, v50
	v_cvt_pk_bf16_f32 v42, v44, v45
	v_or_b32_e32 v44, s24, v51
	v_cvt_pk_bf16_f32 v24, v24, v25
	v_cvt_pk_bf16_f32 v25, v26, v27
	v_cvt_pk_bf16_f32 v26, v28, v29
	v_or_b32_e32 v28, s8, v67
	v_cvt_pk_bf16_f32 v16, v16, v17
	v_cvt_pk_bf16_f32 v17, v18, v19
	v_cvt_pk_bf16_f32 v18, v20, v21
	v_bfi_b32 v20, -4, v66, v88
	v_cvt_pk_bf16_f32 v8, v8, v9
	v_cvt_pk_bf16_f32 v9, v10, v11
	v_cvt_pk_bf16_f32 v10, v12, v13
	v_or_b32_e32 v12, s8, v51
	v_cvt_pk_bf16_f32 v0, v0, v1
	v_cvt_pk_bf16_f32 v1, v2, v3
	v_cvt_pk_bf16_f32 v2, v4, v5
	v_bfi_b32 v4, -4, v50, v88
	v_ashrrev_i32_e32 v45, 31, v44
	v_ashrrev_i32_e32 v29, 31, v28
	v_ashrrev_i32_e32 v21, 31, v20
	v_ashrrev_i32_e32 v13, 31, v12
	v_ashrrev_i32_e32 v5, 31, v4
	v_lshlrev_b64 v[44:45], 19, v[44:45]
	v_lshlrev_b64 v[28:29], 19, v[28:29]
	v_lshlrev_b64 v[20:21], 19, v[20:21]
	v_lshlrev_b64 v[12:13], 19, v[12:13]
	v_lshlrev_b64 v[4:5], 19, v[4:5]
	v_and_b32_e32 v49, 0x7f8, v48
	v_lshl_add_u64 v[44:45], s[0:1], 0, v[44:45]
	v_lshl_add_u64 v[28:29], s[0:1], 0, v[28:29]
	v_lshl_add_u64 v[20:21], s[0:1], 0, v[20:21]
	v_lshl_add_u64 v[12:13], s[0:1], 0, v[12:13]
	v_lshl_add_u64 v[4:5], s[0:1], 0, v[4:5]
	v_cvt_pk_bf16_f32 v57, v62, v63
	v_cvt_pk_bf16_f32 v58, v68, v69
	v_cvt_pk_bf16_f32 v59, v70, v71
	v_lshl_add_u64 v[62:63], v[60:61], 0, v[128:129]
	v_cvt_pk_bf16_f32 v43, v46, v47
	v_lshl_add_u64 v[46:47], v[44:45], 0, v[128:129]
	v_lshlrev_b32_e32 v48, 1, v49
	v_mov_b32_e32 v49, v129
	v_cvt_pk_bf16_f32 v32, v32, v33
	v_cvt_pk_bf16_f32 v33, v34, v35
	v_cvt_pk_bf16_f32 v34, v36, v37
	v_cvt_pk_bf16_f32 v35, v38, v39
	v_lshl_add_u64 v[36:37], v[44:45], 0, v[116:117]
	v_cvt_pk_bf16_f32 v27, v30, v31
	v_lshl_add_u64 v[28:29], v[28:29], 0, v[128:129]
	v_cvt_pk_bf16_f32 v19, v22, v23
	v_lshl_add_u64 v[20:21], v[20:21], 0, v[86:87]
	v_cvt_pk_bf16_f32 v11, v14, v15
	v_lshl_add_u64 v[12:13], v[12:13], 0, v[128:129]
	v_cvt_pk_bf16_f32 v3, v6, v7
	v_lshl_add_u64 v[4:5], v[4:5], 0, v[86:87]
	v_permlane16_swap_b32_e32 v56, v58
	v_permlane16_swap_b32_e32 v57, v59
	v_lshl_add_u64 v[62:63], v[62:63], 0, v[64:65]
	v_permlane16_swap_b32_e32 v40, v42
	v_permlane16_swap_b32_e32 v41, v43
	v_lshl_add_u64 v[46:47], v[46:47], 0, v[48:49]
	v_permlane16_swap_b32_e32 v32, v34
	v_permlane16_swap_b32_e32 v33, v35
	v_lshl_add_u64 v[36:37], v[36:37], 0, v[48:49]
	v_permlane16_swap_b32_e32 v24, v26
	v_permlane16_swap_b32_e32 v25, v27
	v_lshl_add_u64 v[28:29], v[28:29], 0, v[64:65]
	v_permlane16_swap_b32_e32 v16, v18
	v_permlane16_swap_b32_e32 v17, v19
	v_lshl_add_u64 v[20:21], v[20:21], 0, v[64:65]
	v_permlane16_swap_b32_e32 v8, v10
	v_permlane16_swap_b32_e32 v9, v11
	v_lshl_add_u64 v[12:13], v[12:13], 0, v[48:49]
	v_permlane16_swap_b32_e32 v0, v2
	v_permlane16_swap_b32_e32 v1, v3
	v_lshl_add_u64 v[4:5], v[4:5], 0, v[48:49]
	global_store_dwordx4 v[62:63], v[56:59], off nt
	global_store_dwordx4 v[46:47], v[40:43], off nt
	global_store_dwordx4 v[36:37], v[32:35], off nt
	global_store_dwordx4 v[28:29], v[24:27], off nt
	global_store_dwordx4 v[20:21], v[16:19], off nt
	global_store_dwordx4 v[12:13], v[8:11], off nt
	global_store_dwordx4 v[4:5], v[0:3], off nt

.LBB0_638:
	v_lshrrev_b32_e32 v130, 2, v128
	v_and_b32_e32 v130, 8, v130
	v_and_b32_e32 v128, 16, v128
	v_readlane_b32 s1, v253, 18
	v_cvt_pk_bf16_f32 v120, v120, v121
	v_cvt_pk_bf16_f32 v121, v122, v123
	v_or3_b32 v128, v128, v130, s1
	v_or_b32_e32 v132, s0, v128
	v_readlane_b32 s0, v253, 40
	v_or_b32_e32 v128, s8, v147
	v_ashrrev_i32_e32 v133, 31, v132
	v_readlane_b32 s1, v253, 41
	v_cvt_pk_bf16_f32 v122, v124, v125
	v_cvt_pk_bf16_f32 v123, v126, v127
	v_add_u32_e32 v128, s27, v128
	v_cmp_gt_i32_e32 vcc, s71, v132
	v_lshl_add_u64 v[130:131], v[132:133], 1, s[0:1]
	v_permlane16_swap_b32_e32 v120, v122
	v_permlane16_swap_b32_e32 v121, v123
	s_and_saveexec_b64 s[0:1], vcc
	s_cbranch_execz .LBB0_640
	v_mad_u64_u32 v[124:125], s[24:25], v128, s72, v[130:131]
	global_store_dwordx4 v[124:125], v[120:123], off nt
.LBB0_640:
	s_or_b64 exec, exec, s[0:1]
	v_cvt_pk_bf16_f32 v112, v112, v113
	v_cvt_pk_bf16_f32 v113, v114, v115
	v_cvt_pk_bf16_f32 v114, v116, v117
	v_cvt_pk_bf16_f32 v115, v118, v119
	s_nop 0
	v_permlane16_swap_b32_e32 v112, v114
	v_permlane16_swap_b32_e32 v113, v115
	v_or_b32_e32 v116, 16, v128
	s_and_saveexec_b64 s[0:1], vcc
	s_cbranch_execz .LBB0_642
	v_mad_u64_u32 v[118:119], s[24:25], v116, s72, v[130:131]
	global_store_dwordx4 v[118:119], v[112:115], off nt
.LBB0_642:
	s_or_b64 exec, exec, s[0:1]
	v_cvt_pk_bf16_f32 v104, v104, v105
	v_cvt_pk_bf16_f32 v105, v106, v107
	v_cvt_pk_bf16_f32 v106, v108, v109
	v_cvt_pk_bf16_f32 v107, v110, v111
	s_nop 0
	v_permlane16_swap_b32_e32 v104, v106
	v_permlane16_swap_b32_e32 v105, v107
	v_or_b32_e32 v108, 32, v128
	s_and_saveexec_b64 s[0:1], vcc
	s_cbranch_execz .LBB0_644
	v_mad_u64_u32 v[110:111], s[24:25], v108, s72, v[130:131]
	global_store_dwordx4 v[110:111], v[104:107], off nt
.LBB0_644:
	s_or_b64 exec, exec, s[0:1]
	v_cvt_pk_bf16_f32 v96, v96, v97
	v_cvt_pk_bf16_f32 v97, v98, v99
	v_cvt_pk_bf16_f32 v98, v100, v101
	v_cvt_pk_bf16_f32 v99, v102, v103
	s_nop 0
	v_permlane16_swap_b32_e32 v96, v98
	v_permlane16_swap_b32_e32 v97, v99
	v_or_b32_e32 v100, 48, v128
	s_and_saveexec_b64 s[0:1], vcc
	s_cbranch_execz .LBB0_646
	v_mad_u64_u32 v[102:103], s[24:25], v100, s72, v[130:131]
	global_store_dwordx4 v[102:103], v[96:99], off nt
.LBB0_646:
	s_or_b64 exec, exec, s[0:1]
	s_nop 0
	v_or_b32_e32 v96, 0x80, v132
	v_cvt_pk_bf16_f32 v88, v88, v89
	v_cvt_pk_bf16_f32 v89, v90, v91
	v_cvt_pk_bf16_f32 v90, v92, v93
	v_cvt_pk_bf16_f32 v91, v94, v95
	v_cmp_gt_i32_e64 s[0:1], s71, v96
	v_ashrrev_i32_e32 v97, 31, v96
	v_permlane16_swap_b32_e32 v88, v90
	v_permlane16_swap_b32_e32 v89, v91
	s_and_saveexec_b64 s[52:53], s[0:1]
	s_cbranch_execz .LBB0_648
	v_readlane_b32 s24, v253, 40
	v_readlane_b32 s25, v253, 41
	s_nop 1
	v_mov_b64_e32 v[92:93], s[24:25]
	v_mad_u64_u32 v[92:93], s[24:25], v128, s72, v[92:93]
	v_lshl_add_u64 v[92:93], v[96:97], 1, v[92:93]
	global_store_dwordx4 v[92:93], v[88:91], off nt
.LBB0_648:
	s_or_b64 exec, exec, s[52:53]
	v_cvt_pk_bf16_f32 v80, v80, v81
	v_cvt_pk_bf16_f32 v81, v82, v83
	v_cvt_pk_bf16_f32 v82, v84, v85
	v_cvt_pk_bf16_f32 v83, v86, v87
	s_nop 0
	v_permlane16_swap_b32_e32 v80, v82
	v_permlane16_swap_b32_e32 v81, v83
	s_and_saveexec_b64 s[52:53], s[0:1]
	s_cbranch_execz .LBB0_650
	v_readlane_b32 s24, v253, 40
	v_readlane_b32 s25, v253, 41
	s_nop 1
	v_mov_b64_e32 v[84:85], s[24:25]
	v_mad_u64_u32 v[84:85], s[24:25], v116, s72, v[84:85]
	v_lshl_add_u64 v[84:85], v[96:97], 1, v[84:85]
	global_store_dwordx4 v[84:85], v[80:83], off nt
.LBB0_650:
	s_or_b64 exec, exec, s[52:53]
	v_cvt_pk_bf16_f32 v72, v72, v73
	v_cvt_pk_bf16_f32 v73, v74, v75
	v_cvt_pk_bf16_f32 v74, v76, v77
	v_cvt_pk_bf16_f32 v75, v78, v79
	s_nop 0
	v_permlane16_swap_b32_e32 v72, v74
	v_permlane16_swap_b32_e32 v73, v75
	s_and_saveexec_b64 s[52:53], s[0:1]
	s_cbranch_execz .LBB0_652
	v_readlane_b32 s24, v253, 40
	v_readlane_b32 s25, v253, 41
	s_nop 1
	v_mov_b64_e32 v[76:77], s[24:25]
	v_mad_u64_u32 v[76:77], s[24:25], v108, s72, v[76:77]
	v_lshl_add_u64 v[76:77], v[96:97], 1, v[76:77]
	global_store_dwordx4 v[76:77], v[72:75], off nt
.LBB0_652:
	s_or_b64 exec, exec, s[52:53]
	v_cvt_pk_bf16_f32 v64, v64, v65
	v_cvt_pk_bf16_f32 v65, v66, v67
	v_cvt_pk_bf16_f32 v66, v68, v69
	v_cvt_pk_bf16_f32 v67, v70, v71
	s_nop 0
	v_permlane16_swap_b32_e32 v64, v66
	v_permlane16_swap_b32_e32 v65, v67
	s_and_saveexec_b64 s[52:53], s[0:1]
	s_cbranch_execz .LBB0_654
	v_readlane_b32 s24, v253, 40
	v_readlane_b32 s25, v253, 41
	s_nop 1
	v_mov_b64_e32 v[68:69], s[24:25]
	v_mad_u64_u32 v[68:69], s[24:25], v100, s72, v[68:69]
	v_lshl_add_u64 v[68:69], v[96:97], 1, v[68:69]
	global_store_dwordx4 v[68:69], v[64:67], off nt
.LBB0_654:
	s_or_b64 exec, exec, s[52:53]
	v_cvt_pk_bf16_f32 v56, v56, v57
	v_cvt_pk_bf16_f32 v57, v58, v59
	v_cvt_pk_bf16_f32 v58, v60, v61
	v_cvt_pk_bf16_f32 v59, v62, v63
	v_add_u32_e32 v64, 0x80, v128
	v_permlane16_swap_b32_e32 v56, v58
	v_permlane16_swap_b32_e32 v57, v59
	s_and_saveexec_b64 s[52:53], vcc
	s_cbranch_execz .LBB0_656
	v_mad_i64_i32 v[60:61], s[24:25], v64, s72, v[130:131]
	global_store_dwordx4 v[60:61], v[56:59], off nt
.LBB0_656:
	s_or_b64 exec, exec, s[52:53]
	v_cvt_pk_bf16_f32 v48, v48, v49
	v_cvt_pk_bf16_f32 v49, v50, v51
	v_cvt_pk_bf16_f32 v50, v52, v53
	v_cvt_pk_bf16_f32 v51, v54, v55
	s_nop 0
	v_permlane16_swap_b32_e32 v48, v50
	v_permlane16_swap_b32_e32 v49, v51
	v_add_u32_e32 v52, 0x90, v128
	s_and_saveexec_b64 s[52:53], vcc
	s_cbranch_execz .LBB0_658
	v_mad_i64_i32 v[54:55], s[24:25], v52, s72, v[130:131]
	global_store_dwordx4 v[54:55], v[48:51], off nt
.LBB0_658:
	s_or_b64 exec, exec, s[52:53]
	v_cvt_pk_bf16_f32 v40, v40, v41
	v_cvt_pk_bf16_f32 v41, v42, v43
	v_cvt_pk_bf16_f32 v42, v44, v45
	v_cvt_pk_bf16_f32 v43, v46, v47
	s_nop 0
	v_permlane16_swap_b32_e32 v40, v42
	v_permlane16_swap_b32_e32 v41, v43
	v_add_u32_e32 v44, 0xa0, v128
	s_and_saveexec_b64 s[52:53], vcc
	s_cbranch_execz .LBB0_660
	v_mad_i64_i32 v[46:47], s[24:25], v44, s72, v[130:131]
	global_store_dwordx4 v[46:47], v[40:43], off nt
.LBB0_660:
	s_or_b64 exec, exec, s[52:53]
	v_cvt_pk_bf16_f32 v32, v32, v33
	v_cvt_pk_bf16_f32 v33, v34, v35
	v_cvt_pk_bf16_f32 v34, v36, v37
	v_cvt_pk_bf16_f32 v35, v38, v39
	s_nop 0
	v_permlane16_swap_b32_e32 v32, v34
	v_permlane16_swap_b32_e32 v33, v35
	v_add_u32_e32 v36, 0xb0, v128
	s_and_saveexec_b64 s[52:53], vcc
	s_cbranch_execz .LBB0_662
	v_mad_i64_i32 v[38:39], s[24:25], v36, s72, v[130:131]
	global_store_dwordx4 v[38:39], v[32:35], off nt
.LBB0_662:
	s_or_b64 exec, exec, s[52:53]
	v_cvt_pk_bf16_f32 v24, v24, v25
	v_cvt_pk_bf16_f32 v25, v26, v27
	v_cvt_pk_bf16_f32 v26, v28, v29
	v_cvt_pk_bf16_f32 v27, v30, v31
	s_nop 0
	v_permlane16_swap_b32_e32 v24, v26
	v_permlane16_swap_b32_e32 v25, v27
	s_and_saveexec_b64 s[52:53], s[0:1]
	s_cbranch_execz .LBB0_664
	v_readlane_b32 s24, v253, 40
	v_readlane_b32 s25, v253, 41
	s_nop 1
	v_mov_b64_e32 v[28:29], s[24:25]
	v_mad_i64_i32 v[28:29], s[24:25], v64, s72, v[28:29]
	v_lshl_add_u64 v[28:29], v[96:97], 1, v[28:29]
	global_store_dwordx4 v[28:29], v[24:27], off nt
.LBB0_664:
	s_or_b64 exec, exec, s[52:53]
	v_cvt_pk_bf16_f32 v16, v16, v17
	v_cvt_pk_bf16_f32 v17, v18, v19
	v_cvt_pk_bf16_f32 v18, v20, v21
	v_cvt_pk_bf16_f32 v19, v22, v23
	s_nop 0
	v_permlane16_swap_b32_e32 v16, v18
	v_permlane16_swap_b32_e32 v17, v19
	s_and_saveexec_b64 s[52:53], s[0:1]
	s_cbranch_execz .LBB0_666
	v_readlane_b32 s24, v253, 40
	v_readlane_b32 s25, v253, 41
	s_nop 1
	v_mov_b64_e32 v[20:21], s[24:25]
	v_mad_i64_i32 v[20:21], s[24:25], v52, s72, v[20:21]
	v_lshl_add_u64 v[20:21], v[96:97], 1, v[20:21]
	global_store_dwordx4 v[20:21], v[16:19], off nt
.LBB0_666:
	s_or_b64 exec, exec, s[52:53]
	v_cvt_pk_bf16_f32 v8, v8, v9
	v_cvt_pk_bf16_f32 v9, v10, v11
	v_cvt_pk_bf16_f32 v10, v12, v13
	v_cvt_pk_bf16_f32 v11, v14, v15
	s_nop 0
	v_permlane16_swap_b32_e32 v8, v10
	v_permlane16_swap_b32_e32 v9, v11
	s_and_saveexec_b64 s[52:53], s[0:1]
	s_cbranch_execz .LBB0_668
	v_readlane_b32 s24, v253, 40
	v_readlane_b32 s25, v253, 41
	s_nop 1
	v_mov_b64_e32 v[12:13], s[24:25]
	v_mad_i64_i32 v[12:13], s[24:25], v44, s72, v[12:13]
	v_lshl_add_u64 v[12:13], v[96:97], 1, v[12:13]
	global_store_dwordx4 v[12:13], v[8:11], off nt
.LBB0_668:
	s_or_b64 exec, exec, s[52:53]
	v_cvt_pk_bf16_f32 v0, v0, v1
	v_cvt_pk_bf16_f32 v1, v2, v3
	v_cvt_pk_bf16_f32 v2, v4, v5
	v_cvt_pk_bf16_f32 v3, v6, v7
	s_nop 0
	v_permlane16_swap_b32_e32 v0, v2
	v_permlane16_swap_b32_e32 v1, v3
	s_and_saveexec_b64 s[52:53], s[0:1]
	s_cbranch_execz .LBB0_670
	v_readlane_b32 s0, v253, 40
	v_readlane_b32 s1, v253, 41
	s_nop 1
	v_mov_b64_e32 v[4:5], s[0:1]
	v_mad_i64_i32 v[4:5], s[0:1], v36, s72, v[4:5]
	v_lshl_add_u64 v[4:5], v[96:97], 1, v[4:5]
	global_store_dwordx4 v[4:5], v[0:3], off nt

.LBB0_683:
	v_lshrrev_b32_e32 v130, 2, v128
	v_and_b32_e32 v130, 8, v130
	v_and_b32_e32 v128, 16, v128
	v_readlane_b32 s1, v253, 18
	s_add_i32 s55, s55, s27
	v_or_b32_e32 v132, s55, v147
	v_or3_b32 v128, v128, v130, s1
	v_or_b32_e32 v130, s0, v128
	v_ashrrev_i32_e32 v131, 31, v130
	v_lshl_add_u64 v[130:131], v[130:131], 1, s[2:3]
	v_cvt_pk_bf16_f32 v96, v96, v97
	v_cvt_pk_bf16_f32 v97, v98, v99
	v_cvt_pk_bf16_f32 v98, v100, v101
	v_or_b32_e32 v100, 48, v132
	v_cvt_pk_bf16_f32 v56, v56, v57
	v_cvt_pk_bf16_f32 v57, v58, v59
	v_cvt_pk_bf16_f32 v58, v60, v61
	v_cvt_pk_bf16_f32 v59, v62, v63
	v_cvt_pk_bf16_f32 v112, v112, v113
	v_cvt_pk_bf16_f32 v113, v114, v115
	v_cvt_pk_bf16_f32 v114, v116, v117
	v_or_b32_e32 v116, 16, v132
	v_cvt_pk_bf16_f32 v104, v104, v105
	v_cvt_pk_bf16_f32 v105, v106, v107
	v_cvt_pk_bf16_f32 v106, v108, v109
	v_or_b32_e32 v108, 32, v132
	v_mad_i64_i32 v[100:101], s[0:1], v100, s73, v[130:131]
	v_permlane16_swap_b32_e32 v56, v58
	v_permlane16_swap_b32_e32 v57, v59
	v_add_u32_e32 v60, 0x80, v132
	v_cvt_pk_bf16_f32 v48, v48, v49
	v_cvt_pk_bf16_f32 v49, v50, v51
	v_cvt_pk_bf16_f32 v50, v52, v53
	v_add_u32_e32 v52, 0x90, v132
	v_cvt_pk_bf16_f32 v40, v40, v41
	v_cvt_pk_bf16_f32 v41, v42, v43
	v_cvt_pk_bf16_f32 v42, v44, v45
	v_add_u32_e32 v44, 0xa0, v132
	v_cvt_pk_bf16_f32 v32, v32, v33
	v_cvt_pk_bf16_f32 v33, v34, v35
	v_cvt_pk_bf16_f32 v34, v36, v37
	v_add_u32_e32 v36, 0xb0, v132
	v_cvt_pk_bf16_f32 v120, v120, v121
	v_cvt_pk_bf16_f32 v121, v122, v123
	v_cvt_pk_bf16_f32 v122, v124, v125
	v_cvt_pk_bf16_f32 v123, v126, v127
	v_mad_i64_i32 v[124:125], s[0:1], v132, s73, v[130:131]
	v_cvt_pk_bf16_f32 v115, v118, v119
	v_mad_i64_i32 v[116:117], s[0:1], v116, s73, v[130:131]
	v_cvt_pk_bf16_f32 v107, v110, v111
	v_mad_i64_i32 v[108:109], s[0:1], v108, s73, v[130:131]
	v_cvt_pk_bf16_f32 v99, v102, v103
	v_cvt_pk_bf16_f32 v88, v88, v89
	v_cvt_pk_bf16_f32 v89, v90, v91
	v_cvt_pk_bf16_f32 v90, v92, v93
	v_cvt_pk_bf16_f32 v91, v94, v95
	v_cvt_pk_bf16_f32 v80, v80, v81
	v_cvt_pk_bf16_f32 v81, v82, v83
	v_cvt_pk_bf16_f32 v82, v84, v85
	v_cvt_pk_bf16_f32 v83, v86, v87
	v_cvt_pk_bf16_f32 v72, v72, v73
	v_cvt_pk_bf16_f32 v73, v74, v75
	v_cvt_pk_bf16_f32 v74, v76, v77
	v_cvt_pk_bf16_f32 v75, v78, v79
	global_store_dwordx4 v[100:101], v[56:59], off offset:256 nt
	v_mad_i64_i32 v[60:61], s[0:1], v60, s73, v[130:131]
	s_nop 0
	v_cvt_pk_bf16_f32 v56, v64, v65
	v_cvt_pk_bf16_f32 v57, v66, v67
	v_cvt_pk_bf16_f32 v58, v68, v69
	v_cvt_pk_bf16_f32 v59, v70, v71
	v_cvt_pk_bf16_f32 v51, v54, v55
	v_mad_i64_i32 v[52:53], s[0:1], v52, s73, v[130:131]
	v_cvt_pk_bf16_f32 v43, v46, v47
	v_mad_i64_i32 v[44:45], s[0:1], v44, s73, v[130:131]
	v_cvt_pk_bf16_f32 v35, v38, v39
	v_mad_i64_i32 v[36:37], s[0:1], v36, s73, v[130:131]
	v_cvt_pk_bf16_f32 v24, v24, v25
	v_cvt_pk_bf16_f32 v25, v26, v27
	v_cvt_pk_bf16_f32 v26, v28, v29
	v_cvt_pk_bf16_f32 v27, v30, v31
	v_cvt_pk_bf16_f32 v16, v16, v17
	v_cvt_pk_bf16_f32 v17, v18, v19
	v_cvt_pk_bf16_f32 v18, v20, v21
	v_cvt_pk_bf16_f32 v19, v22, v23
	v_cvt_pk_bf16_f32 v8, v8, v9
	v_cvt_pk_bf16_f32 v9, v10, v11
	v_cvt_pk_bf16_f32 v10, v12, v13
	v_cvt_pk_bf16_f32 v11, v14, v15
	v_cvt_pk_bf16_f32 v0, v0, v1
	v_cvt_pk_bf16_f32 v1, v2, v3
	v_cvt_pk_bf16_f32 v2, v4, v5
	v_cvt_pk_bf16_f32 v3, v6, v7
	v_permlane16_swap_b32_e32 v120, v122
	v_permlane16_swap_b32_e32 v121, v123
	v_permlane16_swap_b32_e32 v112, v114
	v_permlane16_swap_b32_e32 v113, v115
	v_permlane16_swap_b32_e32 v104, v106
	v_permlane16_swap_b32_e32 v105, v107
	v_permlane16_swap_b32_e32 v96, v98
	v_permlane16_swap_b32_e32 v97, v99
	v_permlane16_swap_b32_e32 v88, v90
	v_permlane16_swap_b32_e32 v89, v91
	v_permlane16_swap_b32_e32 v80, v82
	v_permlane16_swap_b32_e32 v81, v83
	v_permlane16_swap_b32_e32 v72, v74
	v_permlane16_swap_b32_e32 v73, v75
	v_permlane16_swap_b32_e32 v56, v58
	v_permlane16_swap_b32_e32 v57, v59
	v_permlane16_swap_b32_e32 v48, v50
	v_permlane16_swap_b32_e32 v49, v51
	v_permlane16_swap_b32_e32 v40, v42
	v_permlane16_swap_b32_e32 v41, v43
	v_permlane16_swap_b32_e32 v32, v34
	v_permlane16_swap_b32_e32 v33, v35
	v_permlane16_swap_b32_e32 v24, v26
	v_permlane16_swap_b32_e32 v25, v27
	v_permlane16_swap_b32_e32 v16, v18
	v_permlane16_swap_b32_e32 v17, v19
	v_permlane16_swap_b32_e32 v8, v10
	v_permlane16_swap_b32_e32 v9, v11
	v_permlane16_swap_b32_e32 v0, v2
	v_permlane16_swap_b32_e32 v1, v3
	s_mov_b64 s[0:1], 0
	global_store_dwordx4 v[124:125], v[120:123], off nt
	global_store_dwordx4 v[116:117], v[112:115], off nt
	global_store_dwordx4 v[108:109], v[104:107], off nt
	global_store_dwordx4 v[100:101], v[96:99], off nt
	global_store_dwordx4 v[124:125], v[88:91], off offset:256 nt
	global_store_dwordx4 v[116:117], v[80:83], off offset:256 nt
	global_store_dwordx4 v[108:109], v[72:75], off offset:256 nt
	global_store_dwordx4 v[60:61], v[56:59], off nt
	global_store_dwordx4 v[52:53], v[48:51], off nt
	global_store_dwordx4 v[44:45], v[40:43], off nt
	global_store_dwordx4 v[36:37], v[32:35], off nt
	global_store_dwordx4 v[60:61], v[24:27], off offset:256 nt
	global_store_dwordx4 v[52:53], v[16:19], off offset:256 nt
	global_store_dwordx4 v[44:45], v[8:11], off offset:256 nt
	global_store_dwordx4 v[36:37], v[0:3], off offset:256 nt
